# hand-written SwiGLU epilogue math (3 MQ=4 instances): packed f32 muls in place, no register shuffles; bit-identical formula
# speedup vs baseline: 1.0042x; 1.0017x over previous
.LBB0_479:
	v_lshl_add_u32 v142, s36, 8, v148
	v_ashrrev_i32_e32 v143, 31, v142
	v_lshl_add_u64 v[146:147], v[142:143], 2, s[4:5]
	global_load_dword v241, v[146:147], off
	global_load_dword v242, v[146:147], off offset:64
	global_load_dword v243, v[146:147], off offset:128
	global_load_dword v244, v[146:147], off offset:192
	global_load_dword v245, v[146:147], off offset:512
	global_load_dword v246, v[146:147], off offset:576
	global_load_dword v247, v[146:147], off offset:640
	global_load_dword v248, v[146:147], off offset:704
	v_lshl_or_b32 v144, s22, 7, v150
	v_ashrrev_i32_e32 v145, 31, v144
	v_mov_b32_e32 v254, 1.0
	v_lshl_add_u64 v[144:145], v[144:145], 1, s[6:7]
	s_andn2_b64 vcc, exec, s[38:39]
	v_mad_i64_i32 v[146:147], s[2:3], v142, s60, v[144:145]
	s_waitcnt vmcnt(7)
	v_fmamk_f32 v251, v241, 0x39800000, v155
	v_rsq_f32_e32 v251, v251
	v_pk_mul_f32 v[126:127], v[118:119], v[126:127]
	v_pk_mul_f32 v[128:129], v[120:121], v[128:129]
	v_pk_mul_f32 v[122:123], v[114:115], v[122:123]
	v_pk_mul_f32 v[124:125], v[116:117], v[124:125]
	v_mul_f32_e32 v250, 0xbfb8aa3b, v251
	v_mul_f32_e32 v252, v251, v251
	v_pk_mul_f32 v[118:119], v[118:119], v[250:251] op_sel_hi:[1,0]
	v_pk_mul_f32 v[120:121], v[120:121], v[250:251] op_sel_hi:[1,0]
	v_pk_mul_f32 v[114:115], v[114:115], v[250:251] op_sel_hi:[1,0]
	v_pk_mul_f32 v[116:117], v[116:117], v[250:251] op_sel_hi:[1,0]
	v_exp_f32_e32 v118, v118
	v_exp_f32_e32 v119, v119
	v_exp_f32_e32 v120, v120
	v_exp_f32_e32 v121, v121
	v_exp_f32_e32 v114, v114
	v_exp_f32_e32 v115, v115
	v_exp_f32_e32 v116, v116
	v_exp_f32_e32 v117, v117
	v_pk_add_f32 v[118:119], v[118:119], v[254:255] op_sel_hi:[1,0]
	v_pk_add_f32 v[120:121], v[120:121], v[254:255] op_sel_hi:[1,0]
	v_pk_add_f32 v[114:115], v[114:115], v[254:255] op_sel_hi:[1,0]
	v_pk_add_f32 v[116:117], v[116:117], v[254:255] op_sel_hi:[1,0]
	v_rcp_f32_e32 v118, v118
	v_rcp_f32_e32 v119, v119
	v_rcp_f32_e32 v120, v120
	v_rcp_f32_e32 v121, v121
	v_rcp_f32_e32 v114, v114
	v_rcp_f32_e32 v115, v115
	v_rcp_f32_e32 v116, v116
	v_rcp_f32_e32 v117, v117
	v_pk_mul_f32 v[118:119], v[118:119], v[252:253] op_sel_hi:[1,0]
	v_pk_mul_f32 v[120:121], v[120:121], v[252:253] op_sel_hi:[1,0]
	v_pk_mul_f32 v[114:115], v[114:115], v[252:253] op_sel_hi:[1,0]
	v_pk_mul_f32 v[116:117], v[116:117], v[252:253] op_sel_hi:[1,0]
	v_pk_mul_f32 v[118:119], v[126:127], v[118:119]
	v_pk_mul_f32 v[120:121], v[128:129], v[120:121]
	v_pk_mul_f32 v[114:115], v[122:123], v[114:115]
	v_pk_mul_f32 v[116:117], v[124:125], v[116:117]
	v_cvt_pk_bf16_f32 v122, v118, v119
	v_cvt_pk_bf16_f32 v123, v120, v121
	v_cvt_pk_bf16_f32 v124, v114, v115
	v_cvt_pk_bf16_f32 v125, v116, v117
	global_store_dwordx4 v[146:147], v[122:125], off
	v_add_u32_e32 v253, 16, v142
	v_mad_i64_i32 v[146:147], s[2:3], v253, s60, v[144:145]
	s_waitcnt vmcnt(6)
	v_fmamk_f32 v251, v242, 0x39800000, v155
	v_rsq_f32_e32 v251, v251
	v_pk_mul_f32 v[110:111], v[102:103], v[110:111]
	v_pk_mul_f32 v[112:113], v[104:105], v[112:113]
	v_pk_mul_f32 v[106:107], v[98:99], v[106:107]
	v_pk_mul_f32 v[108:109], v[100:101], v[108:109]
	v_mul_f32_e32 v250, 0xbfb8aa3b, v251
	v_mul_f32_e32 v252, v251, v251
	v_pk_mul_f32 v[102:103], v[102:103], v[250:251] op_sel_hi:[1,0]
	v_pk_mul_f32 v[104:105], v[104:105], v[250:251] op_sel_hi:[1,0]
	v_pk_mul_f32 v[98:99], v[98:99], v[250:251] op_sel_hi:[1,0]
	v_pk_mul_f32 v[100:101], v[100:101], v[250:251] op_sel_hi:[1,0]
	v_exp_f32_e32 v102, v102
	v_exp_f32_e32 v103, v103
	v_exp_f32_e32 v104, v104
	v_exp_f32_e32 v105, v105
	v_exp_f32_e32 v98, v98
	v_exp_f32_e32 v99, v99
	v_exp_f32_e32 v100, v100
	v_exp_f32_e32 v101, v101
	v_pk_add_f32 v[102:103], v[102:103], v[254:255] op_sel_hi:[1,0]
	v_pk_add_f32 v[104:105], v[104:105], v[254:255] op_sel_hi:[1,0]
	v_pk_add_f32 v[98:99], v[98:99], v[254:255] op_sel_hi:[1,0]
	v_pk_add_f32 v[100:101], v[100:101], v[254:255] op_sel_hi:[1,0]
	v_rcp_f32_e32 v102, v102
	v_rcp_f32_e32 v103, v103
	v_rcp_f32_e32 v104, v104
	v_rcp_f32_e32 v105, v105
	v_rcp_f32_e32 v98, v98
	v_rcp_f32_e32 v99, v99
	v_rcp_f32_e32 v100, v100
	v_rcp_f32_e32 v101, v101
	v_pk_mul_f32 v[102:103], v[102:103], v[252:253] op_sel_hi:[1,0]
	v_pk_mul_f32 v[104:105], v[104:105], v[252:253] op_sel_hi:[1,0]
	v_pk_mul_f32 v[98:99], v[98:99], v[252:253] op_sel_hi:[1,0]
	v_pk_mul_f32 v[100:101], v[100:101], v[252:253] op_sel_hi:[1,0]
	v_pk_mul_f32 v[102:103], v[110:111], v[102:103]
	v_pk_mul_f32 v[104:105], v[112:113], v[104:105]
	v_pk_mul_f32 v[98:99], v[106:107], v[98:99]
	v_pk_mul_f32 v[100:101], v[108:109], v[100:101]
	v_cvt_pk_bf16_f32 v106, v102, v103
	v_cvt_pk_bf16_f32 v107, v104, v105
	v_cvt_pk_bf16_f32 v108, v98, v99
	v_cvt_pk_bf16_f32 v109, v100, v101
	global_store_dwordx4 v[146:147], v[106:109], off
	v_add_u32_e32 v253, 32, v142
	v_mad_i64_i32 v[146:147], s[2:3], v253, s60, v[144:145]
	s_waitcnt vmcnt(5)
	v_fmamk_f32 v251, v243, 0x39800000, v155
	v_rsq_f32_e32 v251, v251
	v_pk_mul_f32 v[94:95], v[86:87], v[94:95]
	v_pk_mul_f32 v[96:97], v[88:89], v[96:97]
	v_pk_mul_f32 v[90:91], v[82:83], v[90:91]
	v_pk_mul_f32 v[92:93], v[84:85], v[92:93]
	v_mul_f32_e32 v250, 0xbfb8aa3b, v251
	v_mul_f32_e32 v252, v251, v251
	v_pk_mul_f32 v[86:87], v[86:87], v[250:251] op_sel_hi:[1,0]
	v_pk_mul_f32 v[88:89], v[88:89], v[250:251] op_sel_hi:[1,0]
	v_pk_mul_f32 v[82:83], v[82:83], v[250:251] op_sel_hi:[1,0]
	v_pk_mul_f32 v[84:85], v[84:85], v[250:251] op_sel_hi:[1,0]
	v_exp_f32_e32 v86, v86
	v_exp_f32_e32 v87, v87
	v_exp_f32_e32 v88, v88
	v_exp_f32_e32 v89, v89
	v_exp_f32_e32 v82, v82
	v_exp_f32_e32 v83, v83
	v_exp_f32_e32 v84, v84
	v_exp_f32_e32 v85, v85
	v_pk_add_f32 v[86:87], v[86:87], v[254:255] op_sel_hi:[1,0]
	v_pk_add_f32 v[88:89], v[88:89], v[254:255] op_sel_hi:[1,0]
	v_pk_add_f32 v[82:83], v[82:83], v[254:255] op_sel_hi:[1,0]
	v_pk_add_f32 v[84:85], v[84:85], v[254:255] op_sel_hi:[1,0]
	v_rcp_f32_e32 v86, v86
	v_rcp_f32_e32 v87, v87
	v_rcp_f32_e32 v88, v88
	v_rcp_f32_e32 v89, v89
	v_rcp_f32_e32 v82, v82
	v_rcp_f32_e32 v83, v83
	v_rcp_f32_e32 v84, v84
	v_rcp_f32_e32 v85, v85
	v_pk_mul_f32 v[86:87], v[86:87], v[252:253] op_sel_hi:[1,0]
	v_pk_mul_f32 v[88:89], v[88:89], v[252:253] op_sel_hi:[1,0]
	v_pk_mul_f32 v[82:83], v[82:83], v[252:253] op_sel_hi:[1,0]
	v_pk_mul_f32 v[84:85], v[84:85], v[252:253] op_sel_hi:[1,0]
	v_pk_mul_f32 v[86:87], v[94:95], v[86:87]
	v_pk_mul_f32 v[88:89], v[96:97], v[88:89]
	v_pk_mul_f32 v[82:83], v[90:91], v[82:83]
	v_pk_mul_f32 v[84:85], v[92:93], v[84:85]
	v_cvt_pk_bf16_f32 v90, v86, v87
	v_cvt_pk_bf16_f32 v91, v88, v89
	v_cvt_pk_bf16_f32 v92, v82, v83
	v_cvt_pk_bf16_f32 v93, v84, v85
	global_store_dwordx4 v[146:147], v[90:93], off
	v_add_u32_e32 v253, 48, v142
	v_mad_i64_i32 v[146:147], s[2:3], v253, s60, v[144:145]
	s_waitcnt vmcnt(4)
	v_fmamk_f32 v251, v244, 0x39800000, v155
	v_rsq_f32_e32 v251, v251
	v_pk_mul_f32 v[78:79], v[70:71], v[78:79]
	v_pk_mul_f32 v[80:81], v[72:73], v[80:81]
	v_pk_mul_f32 v[74:75], v[66:67], v[74:75]
	v_pk_mul_f32 v[76:77], v[68:69], v[76:77]
	v_mul_f32_e32 v250, 0xbfb8aa3b, v251
	v_mul_f32_e32 v252, v251, v251
	v_pk_mul_f32 v[70:71], v[70:71], v[250:251] op_sel_hi:[1,0]
	v_pk_mul_f32 v[72:73], v[72:73], v[250:251] op_sel_hi:[1,0]
	v_pk_mul_f32 v[66:67], v[66:67], v[250:251] op_sel_hi:[1,0]
	v_pk_mul_f32 v[68:69], v[68:69], v[250:251] op_sel_hi:[1,0]
	v_exp_f32_e32 v70, v70
	v_exp_f32_e32 v71, v71
	v_exp_f32_e32 v72, v72
	v_exp_f32_e32 v73, v73
	v_exp_f32_e32 v66, v66
	v_exp_f32_e32 v67, v67
	v_exp_f32_e32 v68, v68
	v_exp_f32_e32 v69, v69
	v_pk_add_f32 v[70:71], v[70:71], v[254:255] op_sel_hi:[1,0]
	v_pk_add_f32 v[72:73], v[72:73], v[254:255] op_sel_hi:[1,0]
	v_pk_add_f32 v[66:67], v[66:67], v[254:255] op_sel_hi:[1,0]
	v_pk_add_f32 v[68:69], v[68:69], v[254:255] op_sel_hi:[1,0]
	v_rcp_f32_e32 v70, v70
	v_rcp_f32_e32 v71, v71
	v_rcp_f32_e32 v72, v72
	v_rcp_f32_e32 v73, v73
	v_rcp_f32_e32 v66, v66
	v_rcp_f32_e32 v67, v67
	v_rcp_f32_e32 v68, v68
	v_rcp_f32_e32 v69, v69
	v_pk_mul_f32 v[70:71], v[70:71], v[252:253] op_sel_hi:[1,0]
	v_pk_mul_f32 v[72:73], v[72:73], v[252:253] op_sel_hi:[1,0]
	v_pk_mul_f32 v[66:67], v[66:67], v[252:253] op_sel_hi:[1,0]
	v_pk_mul_f32 v[68:69], v[68:69], v[252:253] op_sel_hi:[1,0]
	v_pk_mul_f32 v[70:71], v[78:79], v[70:71]
	v_pk_mul_f32 v[72:73], v[80:81], v[72:73]
	v_pk_mul_f32 v[66:67], v[74:75], v[66:67]
	v_pk_mul_f32 v[68:69], v[76:77], v[68:69]
	v_cvt_pk_bf16_f32 v74, v70, v71
	v_cvt_pk_bf16_f32 v75, v72, v73
	v_cvt_pk_bf16_f32 v76, v66, v67
	v_cvt_pk_bf16_f32 v77, v68, v69
	global_store_dwordx4 v[146:147], v[74:77], off
	v_add_u32_e32 v253, 128, v142
	v_mad_i64_i32 v[146:147], s[2:3], v253, s60, v[144:145]
	s_waitcnt vmcnt(3)
	v_fmamk_f32 v251, v245, 0x39800000, v155
	v_rsq_f32_e32 v251, v251
	v_pk_mul_f32 v[62:63], v[54:55], v[62:63]
	v_pk_mul_f32 v[64:65], v[56:57], v[64:65]
	v_pk_mul_f32 v[58:59], v[50:51], v[58:59]
	v_pk_mul_f32 v[60:61], v[52:53], v[60:61]
	v_mul_f32_e32 v250, 0xbfb8aa3b, v251
	v_mul_f32_e32 v252, v251, v251
	v_pk_mul_f32 v[54:55], v[54:55], v[250:251] op_sel_hi:[1,0]
	v_pk_mul_f32 v[56:57], v[56:57], v[250:251] op_sel_hi:[1,0]
	v_pk_mul_f32 v[50:51], v[50:51], v[250:251] op_sel_hi:[1,0]
	v_pk_mul_f32 v[52:53], v[52:53], v[250:251] op_sel_hi:[1,0]
	v_exp_f32_e32 v54, v54
	v_exp_f32_e32 v55, v55
	v_exp_f32_e32 v56, v56
	v_exp_f32_e32 v57, v57
	v_exp_f32_e32 v50, v50
	v_exp_f32_e32 v51, v51
	v_exp_f32_e32 v52, v52
	v_exp_f32_e32 v53, v53
	v_pk_add_f32 v[54:55], v[54:55], v[254:255] op_sel_hi:[1,0]
	v_pk_add_f32 v[56:57], v[56:57], v[254:255] op_sel_hi:[1,0]
	v_pk_add_f32 v[50:51], v[50:51], v[254:255] op_sel_hi:[1,0]
	v_pk_add_f32 v[52:53], v[52:53], v[254:255] op_sel_hi:[1,0]
	v_rcp_f32_e32 v54, v54
	v_rcp_f32_e32 v55, v55
	v_rcp_f32_e32 v56, v56
	v_rcp_f32_e32 v57, v57
	v_rcp_f32_e32 v50, v50
	v_rcp_f32_e32 v51, v51
	v_rcp_f32_e32 v52, v52
	v_rcp_f32_e32 v53, v53
	v_pk_mul_f32 v[54:55], v[54:55], v[252:253] op_sel_hi:[1,0]
	v_pk_mul_f32 v[56:57], v[56:57], v[252:253] op_sel_hi:[1,0]
	v_pk_mul_f32 v[50:51], v[50:51], v[252:253] op_sel_hi:[1,0]
	v_pk_mul_f32 v[52:53], v[52:53], v[252:253] op_sel_hi:[1,0]
	v_pk_mul_f32 v[54:55], v[62:63], v[54:55]
	v_pk_mul_f32 v[56:57], v[64:65], v[56:57]
	v_pk_mul_f32 v[50:51], v[58:59], v[50:51]
	v_pk_mul_f32 v[52:53], v[60:61], v[52:53]
	v_cvt_pk_bf16_f32 v58, v54, v55
	v_cvt_pk_bf16_f32 v59, v56, v57
	v_cvt_pk_bf16_f32 v60, v50, v51
	v_cvt_pk_bf16_f32 v61, v52, v53
	global_store_dwordx4 v[146:147], v[58:61], off
	v_add_u32_e32 v253, 144, v142
	v_mad_i64_i32 v[146:147], s[2:3], v253, s60, v[144:145]
	s_waitcnt vmcnt(2)
	v_fmamk_f32 v251, v246, 0x39800000, v155
	v_rsq_f32_e32 v251, v251
	v_pk_mul_f32 v[46:47], v[38:39], v[46:47]
	v_pk_mul_f32 v[48:49], v[40:41], v[48:49]
	v_pk_mul_f32 v[42:43], v[34:35], v[42:43]
	v_pk_mul_f32 v[44:45], v[36:37], v[44:45]
	v_mul_f32_e32 v250, 0xbfb8aa3b, v251
	v_mul_f32_e32 v252, v251, v251
	v_pk_mul_f32 v[38:39], v[38:39], v[250:251] op_sel_hi:[1,0]
	v_pk_mul_f32 v[40:41], v[40:41], v[250:251] op_sel_hi:[1,0]
	v_pk_mul_f32 v[34:35], v[34:35], v[250:251] op_sel_hi:[1,0]
	v_pk_mul_f32 v[36:37], v[36:37], v[250:251] op_sel_hi:[1,0]
	v_exp_f32_e32 v38, v38
	v_exp_f32_e32 v39, v39
	v_exp_f32_e32 v40, v40
	v_exp_f32_e32 v41, v41
	v_exp_f32_e32 v34, v34
	v_exp_f32_e32 v35, v35
	v_exp_f32_e32 v36, v36
	v_exp_f32_e32 v37, v37
	v_pk_add_f32 v[38:39], v[38:39], v[254:255] op_sel_hi:[1,0]
	v_pk_add_f32 v[40:41], v[40:41], v[254:255] op_sel_hi:[1,0]
	v_pk_add_f32 v[34:35], v[34:35], v[254:255] op_sel_hi:[1,0]
	v_pk_add_f32 v[36:37], v[36:37], v[254:255] op_sel_hi:[1,0]
	v_rcp_f32_e32 v38, v38
	v_rcp_f32_e32 v39, v39
	v_rcp_f32_e32 v40, v40
	v_rcp_f32_e32 v41, v41
	v_rcp_f32_e32 v34, v34
	v_rcp_f32_e32 v35, v35
	v_rcp_f32_e32 v36, v36
	v_rcp_f32_e32 v37, v37
	v_pk_mul_f32 v[38:39], v[38:39], v[252:253] op_sel_hi:[1,0]
	v_pk_mul_f32 v[40:41], v[40:41], v[252:253] op_sel_hi:[1,0]
	v_pk_mul_f32 v[34:35], v[34:35], v[252:253] op_sel_hi:[1,0]
	v_pk_mul_f32 v[36:37], v[36:37], v[252:253] op_sel_hi:[1,0]
	v_pk_mul_f32 v[38:39], v[46:47], v[38:39]
	v_pk_mul_f32 v[40:41], v[48:49], v[40:41]
	v_pk_mul_f32 v[34:35], v[42:43], v[34:35]
	v_pk_mul_f32 v[36:37], v[44:45], v[36:37]
	v_cvt_pk_bf16_f32 v42, v38, v39
	v_cvt_pk_bf16_f32 v43, v40, v41
	v_cvt_pk_bf16_f32 v44, v34, v35
	v_cvt_pk_bf16_f32 v45, v36, v37
	global_store_dwordx4 v[146:147], v[42:45], off
	v_add_u32_e32 v253, 160, v142
	v_mad_i64_i32 v[146:147], s[2:3], v253, s60, v[144:145]
	s_waitcnt vmcnt(1)
	v_fmamk_f32 v251, v247, 0x39800000, v155
	v_rsq_f32_e32 v251, v251
	v_pk_mul_f32 v[30:31], v[22:23], v[30:31]
	v_pk_mul_f32 v[32:33], v[24:25], v[32:33]
	v_pk_mul_f32 v[26:27], v[18:19], v[26:27]
	v_pk_mul_f32 v[28:29], v[20:21], v[28:29]
	v_mul_f32_e32 v250, 0xbfb8aa3b, v251
	v_mul_f32_e32 v252, v251, v251
	v_pk_mul_f32 v[22:23], v[22:23], v[250:251] op_sel_hi:[1,0]
	v_pk_mul_f32 v[24:25], v[24:25], v[250:251] op_sel_hi:[1,0]
	v_pk_mul_f32 v[18:19], v[18:19], v[250:251] op_sel_hi:[1,0]
	v_pk_mul_f32 v[20:21], v[20:21], v[250:251] op_sel_hi:[1,0]
	v_exp_f32_e32 v22, v22
	v_exp_f32_e32 v23, v23
	v_exp_f32_e32 v24, v24
	v_exp_f32_e32 v25, v25
	v_exp_f32_e32 v18, v18
	v_exp_f32_e32 v19, v19
	v_exp_f32_e32 v20, v20
	v_exp_f32_e32 v21, v21
	v_pk_add_f32 v[22:23], v[22:23], v[254:255] op_sel_hi:[1,0]
	v_pk_add_f32 v[24:25], v[24:25], v[254:255] op_sel_hi:[1,0]
	v_pk_add_f32 v[18:19], v[18:19], v[254:255] op_sel_hi:[1,0]
	v_pk_add_f32 v[20:21], v[20:21], v[254:255] op_sel_hi:[1,0]
	v_rcp_f32_e32 v22, v22
	v_rcp_f32_e32 v23, v23
	v_rcp_f32_e32 v24, v24
	v_rcp_f32_e32 v25, v25
	v_rcp_f32_e32 v18, v18
	v_rcp_f32_e32 v19, v19
	v_rcp_f32_e32 v20, v20
	v_rcp_f32_e32 v21, v21
	v_pk_mul_f32 v[22:23], v[22:23], v[252:253] op_sel_hi:[1,0]
	v_pk_mul_f32 v[24:25], v[24:25], v[252:253] op_sel_hi:[1,0]
	v_pk_mul_f32 v[18:19], v[18:19], v[252:253] op_sel_hi:[1,0]
	v_pk_mul_f32 v[20:21], v[20:21], v[252:253] op_sel_hi:[1,0]
	v_pk_mul_f32 v[22:23], v[30:31], v[22:23]
	v_pk_mul_f32 v[24:25], v[32:33], v[24:25]
	v_pk_mul_f32 v[18:19], v[26:27], v[18:19]
	v_pk_mul_f32 v[20:21], v[28:29], v[20:21]
	v_cvt_pk_bf16_f32 v26, v22, v23
	v_cvt_pk_bf16_f32 v27, v24, v25
	v_cvt_pk_bf16_f32 v28, v18, v19
	v_cvt_pk_bf16_f32 v29, v20, v21
	global_store_dwordx4 v[146:147], v[26:29], off
	v_add_u32_e32 v253, 176, v142
	v_mad_i64_i32 v[146:147], s[2:3], v253, s60, v[144:145]
	s_mov_b64 s[2:3], -1
	s_waitcnt vmcnt(0)
	v_fmamk_f32 v251, v248, 0x39800000, v155
	v_rsq_f32_e32 v251, v251
	v_pk_mul_f32 v[14:15], v[6:7], v[14:15]
	v_pk_mul_f32 v[16:17], v[8:9], v[16:17]
	v_pk_mul_f32 v[10:11], v[2:3], v[10:11]
	v_pk_mul_f32 v[12:13], v[4:5], v[12:13]
	v_mul_f32_e32 v250, 0xbfb8aa3b, v251
	v_mul_f32_e32 v252, v251, v251
	v_pk_mul_f32 v[6:7], v[6:7], v[250:251] op_sel_hi:[1,0]
	v_pk_mul_f32 v[8:9], v[8:9], v[250:251] op_sel_hi:[1,0]
	v_pk_mul_f32 v[2:3], v[2:3], v[250:251] op_sel_hi:[1,0]
	v_pk_mul_f32 v[4:5], v[4:5], v[250:251] op_sel_hi:[1,0]
	v_exp_f32_e32 v6, v6
	v_exp_f32_e32 v7, v7
	v_exp_f32_e32 v8, v8
	v_exp_f32_e32 v9, v9
	v_exp_f32_e32 v2, v2
	v_exp_f32_e32 v3, v3
	v_exp_f32_e32 v4, v4
	v_exp_f32_e32 v5, v5
	v_pk_add_f32 v[6:7], v[6:7], v[254:255] op_sel_hi:[1,0]
	v_pk_add_f32 v[8:9], v[8:9], v[254:255] op_sel_hi:[1,0]
	v_pk_add_f32 v[2:3], v[2:3], v[254:255] op_sel_hi:[1,0]
	v_pk_add_f32 v[4:5], v[4:5], v[254:255] op_sel_hi:[1,0]
	v_rcp_f32_e32 v6, v6
	v_rcp_f32_e32 v7, v7
	v_rcp_f32_e32 v8, v8
	v_rcp_f32_e32 v9, v9
	v_rcp_f32_e32 v2, v2
	v_rcp_f32_e32 v3, v3
	v_rcp_f32_e32 v4, v4
	v_rcp_f32_e32 v5, v5
	v_pk_mul_f32 v[6:7], v[6:7], v[252:253] op_sel_hi:[1,0]
	v_pk_mul_f32 v[8:9], v[8:9], v[252:253] op_sel_hi:[1,0]
	v_pk_mul_f32 v[2:3], v[2:3], v[252:253] op_sel_hi:[1,0]
	v_pk_mul_f32 v[4:5], v[4:5], v[252:253] op_sel_hi:[1,0]
	v_pk_mul_f32 v[6:7], v[14:15], v[6:7]
	v_pk_mul_f32 v[8:9], v[16:17], v[8:9]
	v_pk_mul_f32 v[2:3], v[10:11], v[2:3]
	v_pk_mul_f32 v[4:5], v[12:13], v[4:5]
	v_cvt_pk_bf16_f32 v10, v6, v7
	v_cvt_pk_bf16_f32 v11, v8, v9
	v_cvt_pk_bf16_f32 v12, v2, v3
	v_cvt_pk_bf16_f32 v13, v4, v5
	global_store_dwordx4 v[146:147], v[10:13], off
	s_cbranch_vccnz .LBB0_401
	s_andn2_b64 vcc, exec, s[0:1]
	s_cbranch_vccnz .LBB0_400
	s_barrier
	s_branch .LBB0_400

.LBB0_1336:
	v_lshl_add_u32 v142, s22, 8, v153
	v_ashrrev_i32_e32 v143, 31, v142
	v_lshl_add_u64 v[146:147], v[142:143], 2, s[4:5]
	global_load_dword v241, v[146:147], off
	global_load_dword v242, v[146:147], off offset:64
	global_load_dword v243, v[146:147], off offset:128
	global_load_dword v244, v[146:147], off offset:192
	global_load_dword v245, v[146:147], off offset:512
	global_load_dword v246, v[146:147], off offset:576
	global_load_dword v247, v[146:147], off offset:640
	global_load_dword v248, v[146:147], off offset:704
	v_lshl_or_b32 v144, s18, 7, v158
	v_ashrrev_i32_e32 v145, 31, v144
	v_mov_b32_e32 v254, 1.0
	v_lshl_add_u64 v[144:145], v[144:145], 1, s[6:7]
	s_andn2_b64 vcc, exec, s[26:27]
	v_mad_i64_i32 v[146:147], s[2:3], v142, s57, v[144:145]
	s_waitcnt vmcnt(7)
	v_fmamk_f32 v251, v241, 0x39800000, v162
	v_rsq_f32_e32 v251, v251
	v_pk_mul_f32 v[126:127], v[118:119], v[126:127]
	v_pk_mul_f32 v[128:129], v[120:121], v[128:129]
	v_pk_mul_f32 v[122:123], v[114:115], v[122:123]
	v_pk_mul_f32 v[124:125], v[116:117], v[124:125]
	v_mul_f32_e32 v250, 0xbfb8aa3b, v251
	v_mul_f32_e32 v252, v251, v251
	v_pk_mul_f32 v[118:119], v[118:119], v[250:251] op_sel_hi:[1,0]
	v_pk_mul_f32 v[120:121], v[120:121], v[250:251] op_sel_hi:[1,0]
	v_pk_mul_f32 v[114:115], v[114:115], v[250:251] op_sel_hi:[1,0]
	v_pk_mul_f32 v[116:117], v[116:117], v[250:251] op_sel_hi:[1,0]
	v_exp_f32_e32 v118, v118
	v_exp_f32_e32 v119, v119
	v_exp_f32_e32 v120, v120
	v_exp_f32_e32 v121, v121
	v_exp_f32_e32 v114, v114
	v_exp_f32_e32 v115, v115
	v_exp_f32_e32 v116, v116
	v_exp_f32_e32 v117, v117
	v_pk_add_f32 v[118:119], v[118:119], v[254:255] op_sel_hi:[1,0]
	v_pk_add_f32 v[120:121], v[120:121], v[254:255] op_sel_hi:[1,0]
	v_pk_add_f32 v[114:115], v[114:115], v[254:255] op_sel_hi:[1,0]
	v_pk_add_f32 v[116:117], v[116:117], v[254:255] op_sel_hi:[1,0]
	v_rcp_f32_e32 v118, v118
	v_rcp_f32_e32 v119, v119
	v_rcp_f32_e32 v120, v120
	v_rcp_f32_e32 v121, v121
	v_rcp_f32_e32 v114, v114
	v_rcp_f32_e32 v115, v115
	v_rcp_f32_e32 v116, v116
	v_rcp_f32_e32 v117, v117
	v_pk_mul_f32 v[118:119], v[118:119], v[252:253] op_sel_hi:[1,0]
	v_pk_mul_f32 v[120:121], v[120:121], v[252:253] op_sel_hi:[1,0]
	v_pk_mul_f32 v[114:115], v[114:115], v[252:253] op_sel_hi:[1,0]
	v_pk_mul_f32 v[116:117], v[116:117], v[252:253] op_sel_hi:[1,0]
	v_pk_mul_f32 v[118:119], v[126:127], v[118:119]
	v_pk_mul_f32 v[120:121], v[128:129], v[120:121]
	v_pk_mul_f32 v[114:115], v[122:123], v[114:115]
	v_pk_mul_f32 v[116:117], v[124:125], v[116:117]
	v_cvt_pk_bf16_f32 v122, v118, v119
	v_cvt_pk_bf16_f32 v123, v120, v121
	v_cvt_pk_bf16_f32 v124, v114, v115
	v_cvt_pk_bf16_f32 v125, v116, v117
	global_store_dwordx4 v[146:147], v[122:125], off
	v_add_u32_e32 v253, 16, v142
	v_mad_i64_i32 v[146:147], s[2:3], v253, s57, v[144:145]
	s_waitcnt vmcnt(6)
	v_fmamk_f32 v251, v242, 0x39800000, v162
	v_rsq_f32_e32 v251, v251
	v_pk_mul_f32 v[110:111], v[102:103], v[110:111]
	v_pk_mul_f32 v[112:113], v[104:105], v[112:113]
	v_pk_mul_f32 v[106:107], v[98:99], v[106:107]
	v_pk_mul_f32 v[108:109], v[100:101], v[108:109]
	v_mul_f32_e32 v250, 0xbfb8aa3b, v251
	v_mul_f32_e32 v252, v251, v251
	v_pk_mul_f32 v[102:103], v[102:103], v[250:251] op_sel_hi:[1,0]
	v_pk_mul_f32 v[104:105], v[104:105], v[250:251] op_sel_hi:[1,0]
	v_pk_mul_f32 v[98:99], v[98:99], v[250:251] op_sel_hi:[1,0]
	v_pk_mul_f32 v[100:101], v[100:101], v[250:251] op_sel_hi:[1,0]
	v_exp_f32_e32 v102, v102
	v_exp_f32_e32 v103, v103
	v_exp_f32_e32 v104, v104
	v_exp_f32_e32 v105, v105
	v_exp_f32_e32 v98, v98
	v_exp_f32_e32 v99, v99
	v_exp_f32_e32 v100, v100
	v_exp_f32_e32 v101, v101
	v_pk_add_f32 v[102:103], v[102:103], v[254:255] op_sel_hi:[1,0]
	v_pk_add_f32 v[104:105], v[104:105], v[254:255] op_sel_hi:[1,0]
	v_pk_add_f32 v[98:99], v[98:99], v[254:255] op_sel_hi:[1,0]
	v_pk_add_f32 v[100:101], v[100:101], v[254:255] op_sel_hi:[1,0]
	v_rcp_f32_e32 v102, v102
	v_rcp_f32_e32 v103, v103
	v_rcp_f32_e32 v104, v104
	v_rcp_f32_e32 v105, v105
	v_rcp_f32_e32 v98, v98
	v_rcp_f32_e32 v99, v99
	v_rcp_f32_e32 v100, v100
	v_rcp_f32_e32 v101, v101
	v_pk_mul_f32 v[102:103], v[102:103], v[252:253] op_sel_hi:[1,0]
	v_pk_mul_f32 v[104:105], v[104:105], v[252:253] op_sel_hi:[1,0]
	v_pk_mul_f32 v[98:99], v[98:99], v[252:253] op_sel_hi:[1,0]
	v_pk_mul_f32 v[100:101], v[100:101], v[252:253] op_sel_hi:[1,0]
	v_pk_mul_f32 v[102:103], v[110:111], v[102:103]
	v_pk_mul_f32 v[104:105], v[112:113], v[104:105]
	v_pk_mul_f32 v[98:99], v[106:107], v[98:99]
	v_pk_mul_f32 v[100:101], v[108:109], v[100:101]
	v_cvt_pk_bf16_f32 v106, v102, v103
	v_cvt_pk_bf16_f32 v107, v104, v105
	v_cvt_pk_bf16_f32 v108, v98, v99
	v_cvt_pk_bf16_f32 v109, v100, v101
	global_store_dwordx4 v[146:147], v[106:109], off
	v_add_u32_e32 v253, 32, v142
	v_mad_i64_i32 v[146:147], s[2:3], v253, s57, v[144:145]
	s_waitcnt vmcnt(5)
	v_fmamk_f32 v251, v243, 0x39800000, v162
	v_rsq_f32_e32 v251, v251
	v_pk_mul_f32 v[94:95], v[86:87], v[94:95]
	v_pk_mul_f32 v[96:97], v[88:89], v[96:97]
	v_pk_mul_f32 v[90:91], v[82:83], v[90:91]
	v_pk_mul_f32 v[92:93], v[84:85], v[92:93]
	v_mul_f32_e32 v250, 0xbfb8aa3b, v251
	v_mul_f32_e32 v252, v251, v251
	v_pk_mul_f32 v[86:87], v[86:87], v[250:251] op_sel_hi:[1,0]
	v_pk_mul_f32 v[88:89], v[88:89], v[250:251] op_sel_hi:[1,0]
	v_pk_mul_f32 v[82:83], v[82:83], v[250:251] op_sel_hi:[1,0]
	v_pk_mul_f32 v[84:85], v[84:85], v[250:251] op_sel_hi:[1,0]
	v_exp_f32_e32 v86, v86
	v_exp_f32_e32 v87, v87
	v_exp_f32_e32 v88, v88
	v_exp_f32_e32 v89, v89
	v_exp_f32_e32 v82, v82
	v_exp_f32_e32 v83, v83
	v_exp_f32_e32 v84, v84
	v_exp_f32_e32 v85, v85
	v_pk_add_f32 v[86:87], v[86:87], v[254:255] op_sel_hi:[1,0]
	v_pk_add_f32 v[88:89], v[88:89], v[254:255] op_sel_hi:[1,0]
	v_pk_add_f32 v[82:83], v[82:83], v[254:255] op_sel_hi:[1,0]
	v_pk_add_f32 v[84:85], v[84:85], v[254:255] op_sel_hi:[1,0]
	v_rcp_f32_e32 v86, v86
	v_rcp_f32_e32 v87, v87
	v_rcp_f32_e32 v88, v88
	v_rcp_f32_e32 v89, v89
	v_rcp_f32_e32 v82, v82
	v_rcp_f32_e32 v83, v83
	v_rcp_f32_e32 v84, v84
	v_rcp_f32_e32 v85, v85
	v_pk_mul_f32 v[86:87], v[86:87], v[252:253] op_sel_hi:[1,0]
	v_pk_mul_f32 v[88:89], v[88:89], v[252:253] op_sel_hi:[1,0]
	v_pk_mul_f32 v[82:83], v[82:83], v[252:253] op_sel_hi:[1,0]
	v_pk_mul_f32 v[84:85], v[84:85], v[252:253] op_sel_hi:[1,0]
	v_pk_mul_f32 v[86:87], v[94:95], v[86:87]
	v_pk_mul_f32 v[88:89], v[96:97], v[88:89]
	v_pk_mul_f32 v[82:83], v[90:91], v[82:83]
	v_pk_mul_f32 v[84:85], v[92:93], v[84:85]
	v_cvt_pk_bf16_f32 v90, v86, v87
	v_cvt_pk_bf16_f32 v91, v88, v89
	v_cvt_pk_bf16_f32 v92, v82, v83
	v_cvt_pk_bf16_f32 v93, v84, v85
	global_store_dwordx4 v[146:147], v[90:93], off
	v_add_u32_e32 v253, 48, v142
	v_mad_i64_i32 v[146:147], s[2:3], v253, s57, v[144:145]
	s_waitcnt vmcnt(4)
	v_fmamk_f32 v251, v244, 0x39800000, v162
	v_rsq_f32_e32 v251, v251
	v_pk_mul_f32 v[78:79], v[70:71], v[78:79]
	v_pk_mul_f32 v[80:81], v[72:73], v[80:81]
	v_pk_mul_f32 v[74:75], v[66:67], v[74:75]
	v_pk_mul_f32 v[76:77], v[68:69], v[76:77]
	v_mul_f32_e32 v250, 0xbfb8aa3b, v251
	v_mul_f32_e32 v252, v251, v251
	v_pk_mul_f32 v[70:71], v[70:71], v[250:251] op_sel_hi:[1,0]
	v_pk_mul_f32 v[72:73], v[72:73], v[250:251] op_sel_hi:[1,0]
	v_pk_mul_f32 v[66:67], v[66:67], v[250:251] op_sel_hi:[1,0]
	v_pk_mul_f32 v[68:69], v[68:69], v[250:251] op_sel_hi:[1,0]
	v_exp_f32_e32 v70, v70
	v_exp_f32_e32 v71, v71
	v_exp_f32_e32 v72, v72
	v_exp_f32_e32 v73, v73
	v_exp_f32_e32 v66, v66
	v_exp_f32_e32 v67, v67
	v_exp_f32_e32 v68, v68
	v_exp_f32_e32 v69, v69
	v_pk_add_f32 v[70:71], v[70:71], v[254:255] op_sel_hi:[1,0]
	v_pk_add_f32 v[72:73], v[72:73], v[254:255] op_sel_hi:[1,0]
	v_pk_add_f32 v[66:67], v[66:67], v[254:255] op_sel_hi:[1,0]
	v_pk_add_f32 v[68:69], v[68:69], v[254:255] op_sel_hi:[1,0]
	v_rcp_f32_e32 v70, v70
	v_rcp_f32_e32 v71, v71
	v_rcp_f32_e32 v72, v72
	v_rcp_f32_e32 v73, v73
	v_rcp_f32_e32 v66, v66
	v_rcp_f32_e32 v67, v67
	v_rcp_f32_e32 v68, v68
	v_rcp_f32_e32 v69, v69
	v_pk_mul_f32 v[70:71], v[70:71], v[252:253] op_sel_hi:[1,0]
	v_pk_mul_f32 v[72:73], v[72:73], v[252:253] op_sel_hi:[1,0]
	v_pk_mul_f32 v[66:67], v[66:67], v[252:253] op_sel_hi:[1,0]
	v_pk_mul_f32 v[68:69], v[68:69], v[252:253] op_sel_hi:[1,0]
	v_pk_mul_f32 v[70:71], v[78:79], v[70:71]
	v_pk_mul_f32 v[72:73], v[80:81], v[72:73]
	v_pk_mul_f32 v[66:67], v[74:75], v[66:67]
	v_pk_mul_f32 v[68:69], v[76:77], v[68:69]
	v_cvt_pk_bf16_f32 v74, v70, v71
	v_cvt_pk_bf16_f32 v75, v72, v73
	v_cvt_pk_bf16_f32 v76, v66, v67
	v_cvt_pk_bf16_f32 v77, v68, v69
	global_store_dwordx4 v[146:147], v[74:77], off
	v_add_u32_e32 v253, 128, v142
	v_mad_i64_i32 v[146:147], s[2:3], v253, s57, v[144:145]
	s_waitcnt vmcnt(3)
	v_fmamk_f32 v251, v245, 0x39800000, v162
	v_rsq_f32_e32 v251, v251
	v_pk_mul_f32 v[62:63], v[54:55], v[62:63]
	v_pk_mul_f32 v[64:65], v[56:57], v[64:65]
	v_pk_mul_f32 v[58:59], v[50:51], v[58:59]
	v_pk_mul_f32 v[60:61], v[52:53], v[60:61]
	v_mul_f32_e32 v250, 0xbfb8aa3b, v251
	v_mul_f32_e32 v252, v251, v251
	v_pk_mul_f32 v[54:55], v[54:55], v[250:251] op_sel_hi:[1,0]
	v_pk_mul_f32 v[56:57], v[56:57], v[250:251] op_sel_hi:[1,0]
	v_pk_mul_f32 v[50:51], v[50:51], v[250:251] op_sel_hi:[1,0]
	v_pk_mul_f32 v[52:53], v[52:53], v[250:251] op_sel_hi:[1,0]
	v_exp_f32_e32 v54, v54
	v_exp_f32_e32 v55, v55
	v_exp_f32_e32 v56, v56
	v_exp_f32_e32 v57, v57
	v_exp_f32_e32 v50, v50
	v_exp_f32_e32 v51, v51
	v_exp_f32_e32 v52, v52
	v_exp_f32_e32 v53, v53
	v_pk_add_f32 v[54:55], v[54:55], v[254:255] op_sel_hi:[1,0]
	v_pk_add_f32 v[56:57], v[56:57], v[254:255] op_sel_hi:[1,0]
	v_pk_add_f32 v[50:51], v[50:51], v[254:255] op_sel_hi:[1,0]
	v_pk_add_f32 v[52:53], v[52:53], v[254:255] op_sel_hi:[1,0]
	v_rcp_f32_e32 v54, v54
	v_rcp_f32_e32 v55, v55
	v_rcp_f32_e32 v56, v56
	v_rcp_f32_e32 v57, v57
	v_rcp_f32_e32 v50, v50
	v_rcp_f32_e32 v51, v51
	v_rcp_f32_e32 v52, v52
	v_rcp_f32_e32 v53, v53
	v_pk_mul_f32 v[54:55], v[54:55], v[252:253] op_sel_hi:[1,0]
	v_pk_mul_f32 v[56:57], v[56:57], v[252:253] op_sel_hi:[1,0]
	v_pk_mul_f32 v[50:51], v[50:51], v[252:253] op_sel_hi:[1,0]
	v_pk_mul_f32 v[52:53], v[52:53], v[252:253] op_sel_hi:[1,0]
	v_pk_mul_f32 v[54:55], v[62:63], v[54:55]
	v_pk_mul_f32 v[56:57], v[64:65], v[56:57]
	v_pk_mul_f32 v[50:51], v[58:59], v[50:51]
	v_pk_mul_f32 v[52:53], v[60:61], v[52:53]
	v_cvt_pk_bf16_f32 v58, v54, v55
	v_cvt_pk_bf16_f32 v59, v56, v57
	v_cvt_pk_bf16_f32 v60, v50, v51
	v_cvt_pk_bf16_f32 v61, v52, v53
	global_store_dwordx4 v[146:147], v[58:61], off
	v_add_u32_e32 v253, 144, v142
	v_mad_i64_i32 v[146:147], s[2:3], v253, s57, v[144:145]
	s_waitcnt vmcnt(2)
	v_fmamk_f32 v251, v246, 0x39800000, v162
	v_rsq_f32_e32 v251, v251
	v_pk_mul_f32 v[46:47], v[38:39], v[46:47]
	v_pk_mul_f32 v[48:49], v[40:41], v[48:49]
	v_pk_mul_f32 v[42:43], v[34:35], v[42:43]
	v_pk_mul_f32 v[44:45], v[36:37], v[44:45]
	v_mul_f32_e32 v250, 0xbfb8aa3b, v251
	v_mul_f32_e32 v252, v251, v251
	v_pk_mul_f32 v[38:39], v[38:39], v[250:251] op_sel_hi:[1,0]
	v_pk_mul_f32 v[40:41], v[40:41], v[250:251] op_sel_hi:[1,0]
	v_pk_mul_f32 v[34:35], v[34:35], v[250:251] op_sel_hi:[1,0]
	v_pk_mul_f32 v[36:37], v[36:37], v[250:251] op_sel_hi:[1,0]
	v_exp_f32_e32 v38, v38
	v_exp_f32_e32 v39, v39
	v_exp_f32_e32 v40, v40
	v_exp_f32_e32 v41, v41
	v_exp_f32_e32 v34, v34
	v_exp_f32_e32 v35, v35
	v_exp_f32_e32 v36, v36
	v_exp_f32_e32 v37, v37
	v_pk_add_f32 v[38:39], v[38:39], v[254:255] op_sel_hi:[1,0]
	v_pk_add_f32 v[40:41], v[40:41], v[254:255] op_sel_hi:[1,0]
	v_pk_add_f32 v[34:35], v[34:35], v[254:255] op_sel_hi:[1,0]
	v_pk_add_f32 v[36:37], v[36:37], v[254:255] op_sel_hi:[1,0]
	v_rcp_f32_e32 v38, v38
	v_rcp_f32_e32 v39, v39
	v_rcp_f32_e32 v40, v40
	v_rcp_f32_e32 v41, v41
	v_rcp_f32_e32 v34, v34
	v_rcp_f32_e32 v35, v35
	v_rcp_f32_e32 v36, v36
	v_rcp_f32_e32 v37, v37
	v_pk_mul_f32 v[38:39], v[38:39], v[252:253] op_sel_hi:[1,0]
	v_pk_mul_f32 v[40:41], v[40:41], v[252:253] op_sel_hi:[1,0]
	v_pk_mul_f32 v[34:35], v[34:35], v[252:253] op_sel_hi:[1,0]
	v_pk_mul_f32 v[36:37], v[36:37], v[252:253] op_sel_hi:[1,0]
	v_pk_mul_f32 v[38:39], v[46:47], v[38:39]
	v_pk_mul_f32 v[40:41], v[48:49], v[40:41]
	v_pk_mul_f32 v[34:35], v[42:43], v[34:35]
	v_pk_mul_f32 v[36:37], v[44:45], v[36:37]
	v_cvt_pk_bf16_f32 v42, v38, v39
	v_cvt_pk_bf16_f32 v43, v40, v41
	v_cvt_pk_bf16_f32 v44, v34, v35
	v_cvt_pk_bf16_f32 v45, v36, v37
	global_store_dwordx4 v[146:147], v[42:45], off
	v_add_u32_e32 v253, 160, v142
	v_mad_i64_i32 v[146:147], s[2:3], v253, s57, v[144:145]
	s_waitcnt vmcnt(1)
	v_fmamk_f32 v251, v247, 0x39800000, v162
	v_rsq_f32_e32 v251, v251
	v_pk_mul_f32 v[30:31], v[22:23], v[30:31]
	v_pk_mul_f32 v[32:33], v[24:25], v[32:33]
	v_pk_mul_f32 v[26:27], v[18:19], v[26:27]
	v_pk_mul_f32 v[28:29], v[20:21], v[28:29]
	v_mul_f32_e32 v250, 0xbfb8aa3b, v251
	v_mul_f32_e32 v252, v251, v251
	v_pk_mul_f32 v[22:23], v[22:23], v[250:251] op_sel_hi:[1,0]
	v_pk_mul_f32 v[24:25], v[24:25], v[250:251] op_sel_hi:[1,0]
	v_pk_mul_f32 v[18:19], v[18:19], v[250:251] op_sel_hi:[1,0]
	v_pk_mul_f32 v[20:21], v[20:21], v[250:251] op_sel_hi:[1,0]
	v_exp_f32_e32 v22, v22
	v_exp_f32_e32 v23, v23
	v_exp_f32_e32 v24, v24
	v_exp_f32_e32 v25, v25
	v_exp_f32_e32 v18, v18
	v_exp_f32_e32 v19, v19
	v_exp_f32_e32 v20, v20
	v_exp_f32_e32 v21, v21
	v_pk_add_f32 v[22:23], v[22:23], v[254:255] op_sel_hi:[1,0]
	v_pk_add_f32 v[24:25], v[24:25], v[254:255] op_sel_hi:[1,0]
	v_pk_add_f32 v[18:19], v[18:19], v[254:255] op_sel_hi:[1,0]
	v_pk_add_f32 v[20:21], v[20:21], v[254:255] op_sel_hi:[1,0]
	v_rcp_f32_e32 v22, v22
	v_rcp_f32_e32 v23, v23
	v_rcp_f32_e32 v24, v24
	v_rcp_f32_e32 v25, v25
	v_rcp_f32_e32 v18, v18
	v_rcp_f32_e32 v19, v19
	v_rcp_f32_e32 v20, v20
	v_rcp_f32_e32 v21, v21
	v_pk_mul_f32 v[22:23], v[22:23], v[252:253] op_sel_hi:[1,0]
	v_pk_mul_f32 v[24:25], v[24:25], v[252:253] op_sel_hi:[1,0]
	v_pk_mul_f32 v[18:19], v[18:19], v[252:253] op_sel_hi:[1,0]
	v_pk_mul_f32 v[20:21], v[20:21], v[252:253] op_sel_hi:[1,0]
	v_pk_mul_f32 v[22:23], v[30:31], v[22:23]
	v_pk_mul_f32 v[24:25], v[32:33], v[24:25]
	v_pk_mul_f32 v[18:19], v[26:27], v[18:19]
	v_pk_mul_f32 v[20:21], v[28:29], v[20:21]
	v_cvt_pk_bf16_f32 v26, v22, v23
	v_cvt_pk_bf16_f32 v27, v24, v25
	v_cvt_pk_bf16_f32 v28, v18, v19
	v_cvt_pk_bf16_f32 v29, v20, v21
	global_store_dwordx4 v[146:147], v[26:29], off
	v_add_u32_e32 v253, 176, v142
	v_mad_i64_i32 v[146:147], s[2:3], v253, s57, v[144:145]
	s_mov_b64 s[2:3], -1
	s_waitcnt vmcnt(0)
	v_fmamk_f32 v251, v248, 0x39800000, v162
	v_rsq_f32_e32 v251, v251
	v_pk_mul_f32 v[14:15], v[6:7], v[14:15]
	v_pk_mul_f32 v[16:17], v[8:9], v[16:17]
	v_pk_mul_f32 v[10:11], v[2:3], v[10:11]
	v_pk_mul_f32 v[12:13], v[4:5], v[12:13]
	v_mul_f32_e32 v250, 0xbfb8aa3b, v251
	v_mul_f32_e32 v252, v251, v251
	v_pk_mul_f32 v[6:7], v[6:7], v[250:251] op_sel_hi:[1,0]
	v_pk_mul_f32 v[8:9], v[8:9], v[250:251] op_sel_hi:[1,0]
	v_pk_mul_f32 v[2:3], v[2:3], v[250:251] op_sel_hi:[1,0]
	v_pk_mul_f32 v[4:5], v[4:5], v[250:251] op_sel_hi:[1,0]
	v_exp_f32_e32 v6, v6
	v_exp_f32_e32 v7, v7
	v_exp_f32_e32 v8, v8
	v_exp_f32_e32 v9, v9
	v_exp_f32_e32 v2, v2
	v_exp_f32_e32 v3, v3
	v_exp_f32_e32 v4, v4
	v_exp_f32_e32 v5, v5
	v_pk_add_f32 v[6:7], v[6:7], v[254:255] op_sel_hi:[1,0]
	v_pk_add_f32 v[8:9], v[8:9], v[254:255] op_sel_hi:[1,0]
	v_pk_add_f32 v[2:3], v[2:3], v[254:255] op_sel_hi:[1,0]
	v_pk_add_f32 v[4:5], v[4:5], v[254:255] op_sel_hi:[1,0]
	v_rcp_f32_e32 v6, v6
	v_rcp_f32_e32 v7, v7
	v_rcp_f32_e32 v8, v8
	v_rcp_f32_e32 v9, v9
	v_rcp_f32_e32 v2, v2
	v_rcp_f32_e32 v3, v3
	v_rcp_f32_e32 v4, v4
	v_rcp_f32_e32 v5, v5
	v_pk_mul_f32 v[6:7], v[6:7], v[252:253] op_sel_hi:[1,0]
	v_pk_mul_f32 v[8:9], v[8:9], v[252:253] op_sel_hi:[1,0]
	v_pk_mul_f32 v[2:3], v[2:3], v[252:253] op_sel_hi:[1,0]
	v_pk_mul_f32 v[4:5], v[4:5], v[252:253] op_sel_hi:[1,0]
	v_pk_mul_f32 v[6:7], v[14:15], v[6:7]
	v_pk_mul_f32 v[8:9], v[16:17], v[8:9]
	v_pk_mul_f32 v[2:3], v[10:11], v[2:3]
	v_pk_mul_f32 v[4:5], v[12:13], v[4:5]
	v_cvt_pk_bf16_f32 v10, v6, v7
	v_cvt_pk_bf16_f32 v11, v8, v9
	v_cvt_pk_bf16_f32 v12, v2, v3
	v_cvt_pk_bf16_f32 v13, v4, v5
	global_store_dwordx4 v[146:147], v[10:13], off
	s_cbranch_vccnz .LBB0_1258
	s_andn2_b64 vcc, exec, s[0:1]
	s_cbranch_vccnz .LBB0_1257
	s_barrier
	s_branch .LBB0_1257

.LBB0_1542:
	v_lshl_add_u32 v142, s18, 8, v153
	v_ashrrev_i32_e32 v143, 31, v142
	v_lshl_add_u64 v[146:147], v[142:143], 2, s[4:5]
	global_load_dword v241, v[146:147], off
	global_load_dword v242, v[146:147], off offset:64
	global_load_dword v243, v[146:147], off offset:128
	global_load_dword v244, v[146:147], off offset:192
	global_load_dword v245, v[146:147], off offset:512
	global_load_dword v246, v[146:147], off offset:576
	global_load_dword v247, v[146:147], off offset:640
	global_load_dword v248, v[146:147], off offset:704
	v_lshl_or_b32 v144, s16, 7, v158
	v_ashrrev_i32_e32 v145, 31, v144
	v_mov_b32_e32 v254, 1.0
	v_lshl_add_u64 v[144:145], v[144:145], 1, s[6:7]
	s_andn2_b64 vcc, exec, s[20:21]
	v_mad_i64_i32 v[146:147], s[2:3], v142, s50, v[144:145]
	s_waitcnt vmcnt(7)
	v_fmamk_f32 v251, v241, 0x39800000, v161
	v_rsq_f32_e32 v251, v251
	v_pk_mul_f32 v[126:127], v[118:119], v[126:127]
	v_pk_mul_f32 v[128:129], v[120:121], v[128:129]
	v_pk_mul_f32 v[122:123], v[114:115], v[122:123]
	v_pk_mul_f32 v[124:125], v[116:117], v[124:125]
	v_mul_f32_e32 v250, 0xbfb8aa3b, v251
	v_mul_f32_e32 v252, v251, v251
	v_pk_mul_f32 v[118:119], v[118:119], v[250:251] op_sel_hi:[1,0]
	v_pk_mul_f32 v[120:121], v[120:121], v[250:251] op_sel_hi:[1,0]
	v_pk_mul_f32 v[114:115], v[114:115], v[250:251] op_sel_hi:[1,0]
	v_pk_mul_f32 v[116:117], v[116:117], v[250:251] op_sel_hi:[1,0]
	v_exp_f32_e32 v118, v118
	v_exp_f32_e32 v119, v119
	v_exp_f32_e32 v120, v120
	v_exp_f32_e32 v121, v121
	v_exp_f32_e32 v114, v114
	v_exp_f32_e32 v115, v115
	v_exp_f32_e32 v116, v116
	v_exp_f32_e32 v117, v117
	v_pk_add_f32 v[118:119], v[118:119], v[254:255] op_sel_hi:[1,0]
	v_pk_add_f32 v[120:121], v[120:121], v[254:255] op_sel_hi:[1,0]
	v_pk_add_f32 v[114:115], v[114:115], v[254:255] op_sel_hi:[1,0]
	v_pk_add_f32 v[116:117], v[116:117], v[254:255] op_sel_hi:[1,0]
	v_rcp_f32_e32 v118, v118
	v_rcp_f32_e32 v119, v119
	v_rcp_f32_e32 v120, v120
	v_rcp_f32_e32 v121, v121
	v_rcp_f32_e32 v114, v114
	v_rcp_f32_e32 v115, v115
	v_rcp_f32_e32 v116, v116
	v_rcp_f32_e32 v117, v117
	v_pk_mul_f32 v[118:119], v[118:119], v[252:253] op_sel_hi:[1,0]
	v_pk_mul_f32 v[120:121], v[120:121], v[252:253] op_sel_hi:[1,0]
	v_pk_mul_f32 v[114:115], v[114:115], v[252:253] op_sel_hi:[1,0]
	v_pk_mul_f32 v[116:117], v[116:117], v[252:253] op_sel_hi:[1,0]
	v_pk_mul_f32 v[118:119], v[126:127], v[118:119]
	v_pk_mul_f32 v[120:121], v[128:129], v[120:121]
	v_pk_mul_f32 v[114:115], v[122:123], v[114:115]
	v_pk_mul_f32 v[116:117], v[124:125], v[116:117]
	v_cvt_pk_bf16_f32 v122, v118, v119
	v_cvt_pk_bf16_f32 v123, v120, v121
	v_cvt_pk_bf16_f32 v124, v114, v115
	v_cvt_pk_bf16_f32 v125, v116, v117
	global_store_dwordx4 v[146:147], v[122:125], off
	v_add_u32_e32 v253, 16, v142
	v_mad_i64_i32 v[146:147], s[2:3], v253, s50, v[144:145]
	s_waitcnt vmcnt(6)
	v_fmamk_f32 v251, v242, 0x39800000, v161
	v_rsq_f32_e32 v251, v251
	v_pk_mul_f32 v[110:111], v[102:103], v[110:111]
	v_pk_mul_f32 v[112:113], v[104:105], v[112:113]
	v_pk_mul_f32 v[106:107], v[98:99], v[106:107]
	v_pk_mul_f32 v[108:109], v[100:101], v[108:109]
	v_mul_f32_e32 v250, 0xbfb8aa3b, v251
	v_mul_f32_e32 v252, v251, v251
	v_pk_mul_f32 v[102:103], v[102:103], v[250:251] op_sel_hi:[1,0]
	v_pk_mul_f32 v[104:105], v[104:105], v[250:251] op_sel_hi:[1,0]
	v_pk_mul_f32 v[98:99], v[98:99], v[250:251] op_sel_hi:[1,0]
	v_pk_mul_f32 v[100:101], v[100:101], v[250:251] op_sel_hi:[1,0]
	v_exp_f32_e32 v102, v102
	v_exp_f32_e32 v103, v103
	v_exp_f32_e32 v104, v104
	v_exp_f32_e32 v105, v105
	v_exp_f32_e32 v98, v98
	v_exp_f32_e32 v99, v99
	v_exp_f32_e32 v100, v100
	v_exp_f32_e32 v101, v101
	v_pk_add_f32 v[102:103], v[102:103], v[254:255] op_sel_hi:[1,0]
	v_pk_add_f32 v[104:105], v[104:105], v[254:255] op_sel_hi:[1,0]
	v_pk_add_f32 v[98:99], v[98:99], v[254:255] op_sel_hi:[1,0]
	v_pk_add_f32 v[100:101], v[100:101], v[254:255] op_sel_hi:[1,0]
	v_rcp_f32_e32 v102, v102
	v_rcp_f32_e32 v103, v103
	v_rcp_f32_e32 v104, v104
	v_rcp_f32_e32 v105, v105
	v_rcp_f32_e32 v98, v98
	v_rcp_f32_e32 v99, v99
	v_rcp_f32_e32 v100, v100
	v_rcp_f32_e32 v101, v101
	v_pk_mul_f32 v[102:103], v[102:103], v[252:253] op_sel_hi:[1,0]
	v_pk_mul_f32 v[104:105], v[104:105], v[252:253] op_sel_hi:[1,0]
	v_pk_mul_f32 v[98:99], v[98:99], v[252:253] op_sel_hi:[1,0]
	v_pk_mul_f32 v[100:101], v[100:101], v[252:253] op_sel_hi:[1,0]
	v_pk_mul_f32 v[102:103], v[110:111], v[102:103]
	v_pk_mul_f32 v[104:105], v[112:113], v[104:105]
	v_pk_mul_f32 v[98:99], v[106:107], v[98:99]
	v_pk_mul_f32 v[100:101], v[108:109], v[100:101]
	v_cvt_pk_bf16_f32 v106, v102, v103
	v_cvt_pk_bf16_f32 v107, v104, v105
	v_cvt_pk_bf16_f32 v108, v98, v99
	v_cvt_pk_bf16_f32 v109, v100, v101
	global_store_dwordx4 v[146:147], v[106:109], off
	v_add_u32_e32 v253, 32, v142
	v_mad_i64_i32 v[146:147], s[2:3], v253, s50, v[144:145]
	s_waitcnt vmcnt(5)
	v_fmamk_f32 v251, v243, 0x39800000, v161
	v_rsq_f32_e32 v251, v251
	v_pk_mul_f32 v[94:95], v[86:87], v[94:95]
	v_pk_mul_f32 v[96:97], v[88:89], v[96:97]
	v_pk_mul_f32 v[90:91], v[82:83], v[90:91]
	v_pk_mul_f32 v[92:93], v[84:85], v[92:93]
	v_mul_f32_e32 v250, 0xbfb8aa3b, v251
	v_mul_f32_e32 v252, v251, v251
	v_pk_mul_f32 v[86:87], v[86:87], v[250:251] op_sel_hi:[1,0]
	v_pk_mul_f32 v[88:89], v[88:89], v[250:251] op_sel_hi:[1,0]
	v_pk_mul_f32 v[82:83], v[82:83], v[250:251] op_sel_hi:[1,0]
	v_pk_mul_f32 v[84:85], v[84:85], v[250:251] op_sel_hi:[1,0]
	v_exp_f32_e32 v86, v86
	v_exp_f32_e32 v87, v87
	v_exp_f32_e32 v88, v88
	v_exp_f32_e32 v89, v89
	v_exp_f32_e32 v82, v82
	v_exp_f32_e32 v83, v83
	v_exp_f32_e32 v84, v84
	v_exp_f32_e32 v85, v85
	v_pk_add_f32 v[86:87], v[86:87], v[254:255] op_sel_hi:[1,0]
	v_pk_add_f32 v[88:89], v[88:89], v[254:255] op_sel_hi:[1,0]
	v_pk_add_f32 v[82:83], v[82:83], v[254:255] op_sel_hi:[1,0]
	v_pk_add_f32 v[84:85], v[84:85], v[254:255] op_sel_hi:[1,0]
	v_rcp_f32_e32 v86, v86
	v_rcp_f32_e32 v87, v87
	v_rcp_f32_e32 v88, v88
	v_rcp_f32_e32 v89, v89
	v_rcp_f32_e32 v82, v82
	v_rcp_f32_e32 v83, v83
	v_rcp_f32_e32 v84, v84
	v_rcp_f32_e32 v85, v85
	v_pk_mul_f32 v[86:87], v[86:87], v[252:253] op_sel_hi:[1,0]
	v_pk_mul_f32 v[88:89], v[88:89], v[252:253] op_sel_hi:[1,0]
	v_pk_mul_f32 v[82:83], v[82:83], v[252:253] op_sel_hi:[1,0]
	v_pk_mul_f32 v[84:85], v[84:85], v[252:253] op_sel_hi:[1,0]
	v_pk_mul_f32 v[86:87], v[94:95], v[86:87]
	v_pk_mul_f32 v[88:89], v[96:97], v[88:89]
	v_pk_mul_f32 v[82:83], v[90:91], v[82:83]
	v_pk_mul_f32 v[84:85], v[92:93], v[84:85]
	v_cvt_pk_bf16_f32 v90, v86, v87
	v_cvt_pk_bf16_f32 v91, v88, v89
	v_cvt_pk_bf16_f32 v92, v82, v83
	v_cvt_pk_bf16_f32 v93, v84, v85
	global_store_dwordx4 v[146:147], v[90:93], off
	v_add_u32_e32 v253, 48, v142
	v_mad_i64_i32 v[146:147], s[2:3], v253, s50, v[144:145]
	s_waitcnt vmcnt(4)
	v_fmamk_f32 v251, v244, 0x39800000, v161
	v_rsq_f32_e32 v251, v251
	v_pk_mul_f32 v[78:79], v[70:71], v[78:79]
	v_pk_mul_f32 v[80:81], v[72:73], v[80:81]
	v_pk_mul_f32 v[74:75], v[66:67], v[74:75]
	v_pk_mul_f32 v[76:77], v[68:69], v[76:77]
	v_mul_f32_e32 v250, 0xbfb8aa3b, v251
	v_mul_f32_e32 v252, v251, v251
	v_pk_mul_f32 v[70:71], v[70:71], v[250:251] op_sel_hi:[1,0]
	v_pk_mul_f32 v[72:73], v[72:73], v[250:251] op_sel_hi:[1,0]
	v_pk_mul_f32 v[66:67], v[66:67], v[250:251] op_sel_hi:[1,0]
	v_pk_mul_f32 v[68:69], v[68:69], v[250:251] op_sel_hi:[1,0]
	v_exp_f32_e32 v70, v70
	v_exp_f32_e32 v71, v71
	v_exp_f32_e32 v72, v72
	v_exp_f32_e32 v73, v73
	v_exp_f32_e32 v66, v66
	v_exp_f32_e32 v67, v67
	v_exp_f32_e32 v68, v68
	v_exp_f32_e32 v69, v69
	v_pk_add_f32 v[70:71], v[70:71], v[254:255] op_sel_hi:[1,0]
	v_pk_add_f32 v[72:73], v[72:73], v[254:255] op_sel_hi:[1,0]
	v_pk_add_f32 v[66:67], v[66:67], v[254:255] op_sel_hi:[1,0]
	v_pk_add_f32 v[68:69], v[68:69], v[254:255] op_sel_hi:[1,0]
	v_rcp_f32_e32 v70, v70
	v_rcp_f32_e32 v71, v71
	v_rcp_f32_e32 v72, v72
	v_rcp_f32_e32 v73, v73
	v_rcp_f32_e32 v66, v66
	v_rcp_f32_e32 v67, v67
	v_rcp_f32_e32 v68, v68
	v_rcp_f32_e32 v69, v69
	v_pk_mul_f32 v[70:71], v[70:71], v[252:253] op_sel_hi:[1,0]
	v_pk_mul_f32 v[72:73], v[72:73], v[252:253] op_sel_hi:[1,0]
	v_pk_mul_f32 v[66:67], v[66:67], v[252:253] op_sel_hi:[1,0]
	v_pk_mul_f32 v[68:69], v[68:69], v[252:253] op_sel_hi:[1,0]
	v_pk_mul_f32 v[70:71], v[78:79], v[70:71]
	v_pk_mul_f32 v[72:73], v[80:81], v[72:73]
	v_pk_mul_f32 v[66:67], v[74:75], v[66:67]
	v_pk_mul_f32 v[68:69], v[76:77], v[68:69]
	v_cvt_pk_bf16_f32 v74, v70, v71
	v_cvt_pk_bf16_f32 v75, v72, v73
	v_cvt_pk_bf16_f32 v76, v66, v67
	v_cvt_pk_bf16_f32 v77, v68, v69
	global_store_dwordx4 v[146:147], v[74:77], off
	v_add_u32_e32 v253, 128, v142
	v_mad_i64_i32 v[146:147], s[2:3], v253, s50, v[144:145]
	s_waitcnt vmcnt(3)
	v_fmamk_f32 v251, v245, 0x39800000, v161
	v_rsq_f32_e32 v251, v251
	v_pk_mul_f32 v[62:63], v[54:55], v[62:63]
	v_pk_mul_f32 v[64:65], v[56:57], v[64:65]
	v_pk_mul_f32 v[58:59], v[50:51], v[58:59]
	v_pk_mul_f32 v[60:61], v[52:53], v[60:61]
	v_mul_f32_e32 v250, 0xbfb8aa3b, v251
	v_mul_f32_e32 v252, v251, v251
	v_pk_mul_f32 v[54:55], v[54:55], v[250:251] op_sel_hi:[1,0]
	v_pk_mul_f32 v[56:57], v[56:57], v[250:251] op_sel_hi:[1,0]
	v_pk_mul_f32 v[50:51], v[50:51], v[250:251] op_sel_hi:[1,0]
	v_pk_mul_f32 v[52:53], v[52:53], v[250:251] op_sel_hi:[1,0]
	v_exp_f32_e32 v54, v54
	v_exp_f32_e32 v55, v55
	v_exp_f32_e32 v56, v56
	v_exp_f32_e32 v57, v57
	v_exp_f32_e32 v50, v50
	v_exp_f32_e32 v51, v51
	v_exp_f32_e32 v52, v52
	v_exp_f32_e32 v53, v53
	v_pk_add_f32 v[54:55], v[54:55], v[254:255] op_sel_hi:[1,0]
	v_pk_add_f32 v[56:57], v[56:57], v[254:255] op_sel_hi:[1,0]
	v_pk_add_f32 v[50:51], v[50:51], v[254:255] op_sel_hi:[1,0]
	v_pk_add_f32 v[52:53], v[52:53], v[254:255] op_sel_hi:[1,0]
	v_rcp_f32_e32 v54, v54
	v_rcp_f32_e32 v55, v55
	v_rcp_f32_e32 v56, v56
	v_rcp_f32_e32 v57, v57
	v_rcp_f32_e32 v50, v50
	v_rcp_f32_e32 v51, v51
	v_rcp_f32_e32 v52, v52
	v_rcp_f32_e32 v53, v53
	v_pk_mul_f32 v[54:55], v[54:55], v[252:253] op_sel_hi:[1,0]
	v_pk_mul_f32 v[56:57], v[56:57], v[252:253] op_sel_hi:[1,0]
	v_pk_mul_f32 v[50:51], v[50:51], v[252:253] op_sel_hi:[1,0]
	v_pk_mul_f32 v[52:53], v[52:53], v[252:253] op_sel_hi:[1,0]
	v_pk_mul_f32 v[54:55], v[62:63], v[54:55]
	v_pk_mul_f32 v[56:57], v[64:65], v[56:57]
	v_pk_mul_f32 v[50:51], v[58:59], v[50:51]
	v_pk_mul_f32 v[52:53], v[60:61], v[52:53]
	v_cvt_pk_bf16_f32 v58, v54, v55
	v_cvt_pk_bf16_f32 v59, v56, v57
	v_cvt_pk_bf16_f32 v60, v50, v51
	v_cvt_pk_bf16_f32 v61, v52, v53
	global_store_dwordx4 v[146:147], v[58:61], off
	v_add_u32_e32 v253, 144, v142
	v_mad_i64_i32 v[146:147], s[2:3], v253, s50, v[144:145]
	s_waitcnt vmcnt(2)
	v_fmamk_f32 v251, v246, 0x39800000, v161
	v_rsq_f32_e32 v251, v251
	v_pk_mul_f32 v[46:47], v[38:39], v[46:47]
	v_pk_mul_f32 v[48:49], v[40:41], v[48:49]
	v_pk_mul_f32 v[42:43], v[34:35], v[42:43]
	v_pk_mul_f32 v[44:45], v[36:37], v[44:45]
	v_mul_f32_e32 v250, 0xbfb8aa3b, v251
	v_mul_f32_e32 v252, v251, v251
	v_pk_mul_f32 v[38:39], v[38:39], v[250:251] op_sel_hi:[1,0]
	v_pk_mul_f32 v[40:41], v[40:41], v[250:251] op_sel_hi:[1,0]
	v_pk_mul_f32 v[34:35], v[34:35], v[250:251] op_sel_hi:[1,0]
	v_pk_mul_f32 v[36:37], v[36:37], v[250:251] op_sel_hi:[1,0]
	v_exp_f32_e32 v38, v38
	v_exp_f32_e32 v39, v39
	v_exp_f32_e32 v40, v40
	v_exp_f32_e32 v41, v41
	v_exp_f32_e32 v34, v34
	v_exp_f32_e32 v35, v35
	v_exp_f32_e32 v36, v36
	v_exp_f32_e32 v37, v37
	v_pk_add_f32 v[38:39], v[38:39], v[254:255] op_sel_hi:[1,0]
	v_pk_add_f32 v[40:41], v[40:41], v[254:255] op_sel_hi:[1,0]
	v_pk_add_f32 v[34:35], v[34:35], v[254:255] op_sel_hi:[1,0]
	v_pk_add_f32 v[36:37], v[36:37], v[254:255] op_sel_hi:[1,0]
	v_rcp_f32_e32 v38, v38
	v_rcp_f32_e32 v39, v39
	v_rcp_f32_e32 v40, v40
	v_rcp_f32_e32 v41, v41
	v_rcp_f32_e32 v34, v34
	v_rcp_f32_e32 v35, v35
	v_rcp_f32_e32 v36, v36
	v_rcp_f32_e32 v37, v37
	v_pk_mul_f32 v[38:39], v[38:39], v[252:253] op_sel_hi:[1,0]
	v_pk_mul_f32 v[40:41], v[40:41], v[252:253] op_sel_hi:[1,0]
	v_pk_mul_f32 v[34:35], v[34:35], v[252:253] op_sel_hi:[1,0]
	v_pk_mul_f32 v[36:37], v[36:37], v[252:253] op_sel_hi:[1,0]
	v_pk_mul_f32 v[38:39], v[46:47], v[38:39]
	v_pk_mul_f32 v[40:41], v[48:49], v[40:41]
	v_pk_mul_f32 v[34:35], v[42:43], v[34:35]
	v_pk_mul_f32 v[36:37], v[44:45], v[36:37]
	v_cvt_pk_bf16_f32 v42, v38, v39
	v_cvt_pk_bf16_f32 v43, v40, v41
	v_cvt_pk_bf16_f32 v44, v34, v35
	v_cvt_pk_bf16_f32 v45, v36, v37
	global_store_dwordx4 v[146:147], v[42:45], off
	v_add_u32_e32 v253, 160, v142
	v_mad_i64_i32 v[146:147], s[2:3], v253, s50, v[144:145]
	s_waitcnt vmcnt(1)
	v_fmamk_f32 v251, v247, 0x39800000, v161
	v_rsq_f32_e32 v251, v251
	v_pk_mul_f32 v[30:31], v[22:23], v[30:31]
	v_pk_mul_f32 v[32:33], v[24:25], v[32:33]
	v_pk_mul_f32 v[26:27], v[18:19], v[26:27]
	v_pk_mul_f32 v[28:29], v[20:21], v[28:29]
	v_mul_f32_e32 v250, 0xbfb8aa3b, v251
	v_mul_f32_e32 v252, v251, v251
	v_pk_mul_f32 v[22:23], v[22:23], v[250:251] op_sel_hi:[1,0]
	v_pk_mul_f32 v[24:25], v[24:25], v[250:251] op_sel_hi:[1,0]
	v_pk_mul_f32 v[18:19], v[18:19], v[250:251] op_sel_hi:[1,0]
	v_pk_mul_f32 v[20:21], v[20:21], v[250:251] op_sel_hi:[1,0]
	v_exp_f32_e32 v22, v22
	v_exp_f32_e32 v23, v23
	v_exp_f32_e32 v24, v24
	v_exp_f32_e32 v25, v25
	v_exp_f32_e32 v18, v18
	v_exp_f32_e32 v19, v19
	v_exp_f32_e32 v20, v20
	v_exp_f32_e32 v21, v21
	v_pk_add_f32 v[22:23], v[22:23], v[254:255] op_sel_hi:[1,0]
	v_pk_add_f32 v[24:25], v[24:25], v[254:255] op_sel_hi:[1,0]
	v_pk_add_f32 v[18:19], v[18:19], v[254:255] op_sel_hi:[1,0]
	v_pk_add_f32 v[20:21], v[20:21], v[254:255] op_sel_hi:[1,0]
	v_rcp_f32_e32 v22, v22
	v_rcp_f32_e32 v23, v23
	v_rcp_f32_e32 v24, v24
	v_rcp_f32_e32 v25, v25
	v_rcp_f32_e32 v18, v18
	v_rcp_f32_e32 v19, v19
	v_rcp_f32_e32 v20, v20
	v_rcp_f32_e32 v21, v21
	v_pk_mul_f32 v[22:23], v[22:23], v[252:253] op_sel_hi:[1,0]
	v_pk_mul_f32 v[24:25], v[24:25], v[252:253] op_sel_hi:[1,0]
	v_pk_mul_f32 v[18:19], v[18:19], v[252:253] op_sel_hi:[1,0]
	v_pk_mul_f32 v[20:21], v[20:21], v[252:253] op_sel_hi:[1,0]
	v_pk_mul_f32 v[22:23], v[30:31], v[22:23]
	v_pk_mul_f32 v[24:25], v[32:33], v[24:25]
	v_pk_mul_f32 v[18:19], v[26:27], v[18:19]
	v_pk_mul_f32 v[20:21], v[28:29], v[20:21]
	v_cvt_pk_bf16_f32 v26, v22, v23
	v_cvt_pk_bf16_f32 v27, v24, v25
	v_cvt_pk_bf16_f32 v28, v18, v19
	v_cvt_pk_bf16_f32 v29, v20, v21
	global_store_dwordx4 v[146:147], v[26:29], off
	v_add_u32_e32 v253, 176, v142
	v_mad_i64_i32 v[146:147], s[2:3], v253, s50, v[144:145]
	s_mov_b64 s[2:3], -1
	s_waitcnt vmcnt(0)
	v_fmamk_f32 v251, v248, 0x39800000, v161
	v_rsq_f32_e32 v251, v251
	v_pk_mul_f32 v[14:15], v[6:7], v[14:15]
	v_pk_mul_f32 v[16:17], v[8:9], v[16:17]
	v_pk_mul_f32 v[10:11], v[2:3], v[10:11]
	v_pk_mul_f32 v[12:13], v[4:5], v[12:13]
	v_mul_f32_e32 v250, 0xbfb8aa3b, v251
	v_mul_f32_e32 v252, v251, v251
	v_pk_mul_f32 v[6:7], v[6:7], v[250:251] op_sel_hi:[1,0]
	v_pk_mul_f32 v[8:9], v[8:9], v[250:251] op_sel_hi:[1,0]
	v_pk_mul_f32 v[2:3], v[2:3], v[250:251] op_sel_hi:[1,0]
	v_pk_mul_f32 v[4:5], v[4:5], v[250:251] op_sel_hi:[1,0]
	v_exp_f32_e32 v6, v6
	v_exp_f32_e32 v7, v7
	v_exp_f32_e32 v8, v8
	v_exp_f32_e32 v9, v9
	v_exp_f32_e32 v2, v2
	v_exp_f32_e32 v3, v3
	v_exp_f32_e32 v4, v4
	v_exp_f32_e32 v5, v5
	v_pk_add_f32 v[6:7], v[6:7], v[254:255] op_sel_hi:[1,0]
	v_pk_add_f32 v[8:9], v[8:9], v[254:255] op_sel_hi:[1,0]
	v_pk_add_f32 v[2:3], v[2:3], v[254:255] op_sel_hi:[1,0]
	v_pk_add_f32 v[4:5], v[4:5], v[254:255] op_sel_hi:[1,0]
	v_rcp_f32_e32 v6, v6
	v_rcp_f32_e32 v7, v7
	v_rcp_f32_e32 v8, v8
	v_rcp_f32_e32 v9, v9
	v_rcp_f32_e32 v2, v2
	v_rcp_f32_e32 v3, v3
	v_rcp_f32_e32 v4, v4
	v_rcp_f32_e32 v5, v5
	v_pk_mul_f32 v[6:7], v[6:7], v[252:253] op_sel_hi:[1,0]
	v_pk_mul_f32 v[8:9], v[8:9], v[252:253] op_sel_hi:[1,0]
	v_pk_mul_f32 v[2:3], v[2:3], v[252:253] op_sel_hi:[1,0]
	v_pk_mul_f32 v[4:5], v[4:5], v[252:253] op_sel_hi:[1,0]
	v_pk_mul_f32 v[6:7], v[14:15], v[6:7]
	v_pk_mul_f32 v[8:9], v[16:17], v[8:9]
	v_pk_mul_f32 v[2:3], v[10:11], v[2:3]
	v_pk_mul_f32 v[4:5], v[12:13], v[4:5]
	v_cvt_pk_bf16_f32 v10, v6, v7
	v_cvt_pk_bf16_f32 v11, v8, v9
	v_cvt_pk_bf16_f32 v12, v2, v3
	v_cvt_pk_bf16_f32 v13, v4, v5
	global_store_dwordx4 v[146:147], v[10:13], off
	s_cbranch_vccnz .LBB0_1464
	s_andn2_b64 vcc, exec, s[0:1]
	s_cbranch_vccnz .LBB0_1463
	s_barrier
	s_branch .LBB0_1463

	.amdhsa_kernel _Z8skel_fwd4Args
		.amdhsa_group_segment_fixed_size 0
		.amdhsa_private_segment_fixed_size 0
		.amdhsa_kernarg_size 448
		.amdhsa_user_sgpr_count 2
		.amdhsa_user_sgpr_dispatch_ptr 0
		.amdhsa_user_sgpr_queue_ptr 0
		.amdhsa_user_sgpr_kernarg_segment_ptr 1
		.amdhsa_user_sgpr_dispatch_id 0
		.amdhsa_user_sgpr_kernarg_preload_length 0
		.amdhsa_user_sgpr_kernarg_preload_offset 0
		.amdhsa_user_sgpr_private_segment_size 0
		.amdhsa_uses_dynamic_stack 0
		.amdhsa_enable_private_segment 0
		.amdhsa_system_sgpr_workgroup_id_x 1
		.amdhsa_system_sgpr_workgroup_id_y 0
		.amdhsa_system_sgpr_workgroup_id_z 0
		.amdhsa_system_sgpr_workgroup_info 0
		.amdhsa_system_vgpr_workitem_id 0
		.amdhsa_next_free_vgpr 256
		.amdhsa_next_free_sgpr 102
		.amdhsa_accum_offset 256
		.amdhsa_reserve_vcc 1
		.amdhsa_float_round_mode_32 0
		.amdhsa_float_round_mode_16_64 0
		.amdhsa_float_denorm_mode_32 3
		.amdhsa_float_denorm_mode_16_64 3
		.amdhsa_dx10_clamp 1
		.amdhsa_ieee_mode 1
		.amdhsa_fp16_overflow 0
		.amdhsa_tg_split 0
		.amdhsa_exception_fp_ieee_invalid_op 0
		.amdhsa_exception_fp_denorm_src 0
		.amdhsa_exception_fp_ieee_div_zero 0
		.amdhsa_exception_fp_ieee_overflow 0
		.amdhsa_exception_fp_ieee_underflow 0
		.amdhsa_exception_fp_ieee_inexact 0
		.amdhsa_exception_int_div_zero 0
	.end_amdhsa_kernel

amdhsa.kernels:
  - .agpr_count:     0
    .args:
      - .offset:         0
        .size:           192
        .value_kind:     by_value
      - .offset:         192
        .size:           4
        .value_kind:     hidden_block_count_x
      - .offset:         196
        .size:           4
        .value_kind:     hidden_block_count_y
      - .offset:         200
        .size:           4
        .value_kind:     hidden_block_count_z
      - .offset:         204
        .size:           2
        .value_kind:     hidden_group_size_x
      - .offset:         206
        .size:           2
        .value_kind:     hidden_group_size_y
      - .offset:         208
        .size:           2
        .value_kind:     hidden_group_size_z
      - .offset:         210
        .size:           2
        .value_kind:     hidden_remainder_x
      - .offset:         212
        .size:           2
        .value_kind:     hidden_remainder_y
      - .offset:         214
        .size:           2
        .value_kind:     hidden_remainder_z
      - .offset:         232
        .size:           8
        .value_kind:     hidden_global_offset_x
      - .offset:         240
        .size:           8
        .value_kind:     hidden_global_offset_y
      - .offset:         248
        .size:           8
        .value_kind:     hidden_global_offset_z
      - .offset:         256
        .size:           2
        .value_kind:     hidden_grid_dims
      - .offset:         312
        .size:           4
        .value_kind:     hidden_dynamic_lds_size
    .group_segment_fixed_size: 0
    .kernarg_segment_align: 8
    .kernarg_segment_size: 448
    .language:       OpenCL C
    .language_version:
      - 2
      - 0
    .max_flat_workgroup_size: 512
    .name:           _Z8skel_fwd4Args
    .private_segment_fixed_size: 0
    .sgpr_count:     108
    .sgpr_spill_count: 29
    .symbol:         _Z8skel_fwd4Args.kd
    .uniform_work_group_size: 1
    .uses_dynamic_stack: false
    .vgpr_count:     256
    .vgpr_spill_count: 0
    .wavefront_size: 64
